# back-edge rotation (docs 7.11) on the GQA and MLA attention loops: loop-bottom barrier becomes the loop head
# baseline (speedup 1.0000x reference)
.LBB0_691:
	s_and_b32 s6, s9, 3
	s_mul_i32 s10, s8, 0x900
	s_mul_hi_u32 s7, s8, 0x900
	s_add_u32 s0, s10, s0
	s_addc_u32 s1, s7, s1
	s_mulk_i32 s1, 0xf40
	s_mul_hi_u32 s7, s0, 0xf40
	s_add_i32 s7, s7, s1
	s_mulk_i32 s0, 0xf40
	s_add_u32 s0, s80, s0
	s_addc_u32 s1, s81, s7
	s_lshl_b32 s6, s6, 7
	s_add_u32 s6, s0, s6
	s_addc_u32 s7, s1, 0
	s_mul_i32 s1, s8, 0x894000
	s_mul_hi_u32 s0, s8, 0x894000
	s_add_u32 s1, s80, s1
	s_addc_u32 s10, s81, s0
	s_lshl_b32 s0, s9, 6
	s_and_b32 s12, s0, 0x80
	s_add_u32 s0, s1, s12
	v_mov_b32_e32 v111, v211
	s_addc_u32 s1, s10, 0
	v_mov_b64_e32 v[50:51], s[0:1]
	v_lshlrev_b32_e32 v16, 3, v111
	v_ashrrev_i32_e32 v92, 4, v111
	v_ashrrev_i32_e32 v93, 3, v111
	v_and_b32_e32 v0, 56, v16
	v_lshlrev_b32_e32 v17, 4, v111
	v_mad_i64_i32 v[2:3], s[0:1], v93, s95, v[50:51]
	v_lshlrev_b32_e32 v52, 1, v0
	v_mov_b32_e32 v53, v1
	v_mad_i64_i32 v[4:5], s[0:1], v92, s95, v[50:51]
	v_and_b32_e32 v90, 0xf0, v17
	v_mov_b32_e32 v91, v1
	v_lshl_add_u64 v[2:3], v[2:3], 0, v[52:53]
	v_lshl_add_u64 v[6:7], v[4:5], 0, v[90:91]
	s_waitcnt vmcnt(0)
	v_add_u32_e32 v18, 32, v92
	global_load_dwordx4 v[2:5], v[2:3], off offset:3648
	s_nop 0
	global_load_dwordx4 v[6:9], v[6:7], off offset:3392
	v_mad_i64_i32 v[10:11], s[0:1], v18, s95, v[50:51]
	v_lshl_add_u64 v[10:11], v[10:11], 0, v[90:91]
	global_load_dwordx4 v[10:13], v[10:11], off offset:3392
	v_ashrrev_i32_e32 v19, 1, v111
	s_movk_i32 s0, 0xffe0
	v_bfe_u32 v130, v111, 5, 1
	v_bfi_b32 v0, s0, v19, v111
	v_mov_b64_e32 v[14:15], s[6:7]
	v_mad_i64_i32 v[14:15], s[0:1], v0, s95, v[14:15]
	v_lshlrev_b32_e32 v0, 4, v130
	v_lshl_add_u64 v[14:15], v[14:15], 0, v[0:1]
	global_load_dwordx4 v[78:81], v[14:15], off offset:2880
	global_load_dwordx4 v[70:73], v[14:15], off offset:2912
	global_load_dwordx4 v[66:69], v[14:15], off offset:2944
	global_load_dwordx4 v[74:77], v[14:15], off offset:2976
	v_and_b32_e32 v21, 0x1fffff0, v93
	v_lshlrev_b32_e32 v22, 1, v93
	v_lshrrev_b32_e32 v23, 1, v93
	v_and_b32_e32 v24, 3, v93
	v_and_or_b32 v21, v22, 8, v21
	v_and_b32_e32 v131, 31, v111
	v_bfe_u32 v16, v16, 5, 1
	v_and_b32_e32 v25, 48, v17
	v_and_or_b32 v22, v23, 4, v24
	v_lshrrev_b32_e32 v21, 2, v21
	v_lshlrev_b32_e32 v82, 8, v131
	v_and_b32_e32 v83, 0x70, v17
	v_lshl_or_b32 v22, v22, 6, v25
	v_or_b32_e32 v16, v21, v16
	v_and_b32_e32 v20, 0x70, v111
	v_lshlrev_b32_e32 v26, 8, v92
	v_lshlrev_b32_e32 v18, 8, v18
	v_bitop3_b32 v24, v0, v82, v83 bitop3:0xde
	v_lshl_or_b32 v14, v16, 9, v22
	v_bitop3_b32 v23, v90, v26, v20 bitop3:0xde
	v_bitop3_b32 v18, v90, v18, v20 bitop3:0xde
	v_add_u32_e32 v138, 0, v24
	v_add_u32_e32 v141, 0, v14
	v_add_u32_e32 v139, 0, v23
	v_add_u32_e32 v140, 0, v18
	s_waitcnt vmcnt(0)
	v_and_b32_e32 v134, 63, v111
	v_and_b32_e32 v132, 0xffffffe0, v19
	v_readlane_b32 s36, v252, 0
	v_readlane_b32 s37, v252, 1
	s_mov_b32 s13, s37
	s_cmp_lg_u32 0, -1
	v_mad_i64_i32 v[124:125], s[0:1], v93, s95, 0
	v_mad_i64_i32 v[122:123], s[0:1], v92, s95, 0
	s_cselect_b32 s9, 0, 0
	v_readlane_b32 s38, v252, 2
	v_readlane_b32 s39, v252, 3
	s_waitcnt vmcnt(0)
	ds_write_b128 v141, v[2:5]
	ds_write_b128 v139, v[6:9] offset:16384
	ds_write_b128 v140, v[10:13] offset:16384
	s_waitcnt lgkmcnt(0)
	s_barrier
	ds_read_b128 v[2:5], v138 offset:16384
	v_and_b32_e32 v6, 0x3fffffc0, v111
	v_lshl_add_u32 v133, v6, 2, 0
	ds_read_b128 v[6:9], v138 offset:24576
	s_waitcnt lgkmcnt(1)
	v_mfma_f32_32x32x16_bf16 v[34:49], v[2:5], v[78:81], 0
	v_or_b32_e32 v2, 32, v0
	v_bitop3_b32 v2, v2, v82, v83 bitop3:0xde
	v_add_u32_e32 v142, 0, v2
	ds_read_b128 v[2:5], v142 offset:16384
	v_lshlrev_b32_e32 v10, 1, v111
	v_lshlrev_b32_e32 v11, 3, v134
	v_and_b32_e32 v12, 0xc0, v17
	s_waitcnt lgkmcnt(1)
	v_mfma_f32_32x32x16_bf16 v[18:33], v[6:9], v[78:81], 0
	v_and_b32_e32 v6, 32, v10
	v_and_or_b32 v7, v11, 24, v12
	v_and_b32_e32 v8, 0x100, v11
	v_or3_b32 v135, v7, v6, v8
	ds_read_b128 v[6:9], v142 offset:24576
	v_readlane_b32 s40, v252, 4
	v_readlane_b32 s41, v252, 5
	s_waitcnt lgkmcnt(1)
	v_mfma_f32_32x32x16_bf16 v[34:49], v[2:5], v[70:73], v[34:49]
	v_or_b32_e32 v2, 64, v0
	v_bitop3_b32 v10, v2, v82, v83 bitop3:0xde
	v_add_u32_e32 v2, 64, v93
	v_mad_i64_i32 v[2:3], s[0:1], v2, s95, v[50:51]
	v_add_u32_e32 v4, 64, v92
	v_lshl_add_u64 v[2:3], v[2:3], 0, v[52:53]
	v_mad_i64_i32 v[4:5], s[0:1], v4, s95, v[50:51]
	v_lshl_add_u64 v[4:5], v[4:5], 0, v[90:91]
	global_load_dwordx4 v[54:57], v[2:3], off offset:3648
	global_load_dwordx4 v[58:61], v[4:5], off offset:3392
	v_add_u32_e32 v2, 0x60, v92
	v_mad_i64_i32 v[2:3], s[0:1], v2, s95, v[50:51]
	v_lshl_add_u64 v[2:3], v[2:3], 0, v[90:91]
	v_add_u32_e32 v144, 0, v10
	global_load_dwordx4 v[62:65], v[2:3], off offset:3392
	ds_read_b128 v[2:5], v144 offset:16384
	s_waitcnt lgkmcnt(1)
	v_mfma_f32_32x32x16_bf16 v[18:33], v[6:9], v[70:73], v[18:33]
	ds_read_b128 v[6:9], v144 offset:24576
	s_mov_b64 s[0:1], s[12:13]
	v_readlane_b32 s42, v252, 6
	v_readlane_b32 s43, v252, 7
	v_readlane_b32 s44, v252, 8
	v_readlane_b32 s45, v252, 9
	v_readlane_b32 s46, v252, 10
	s_waitcnt lgkmcnt(1)
	v_mfma_f32_32x32x16_bf16 v[34:49], v[2:5], v[66:69], v[34:49]
	v_or_b32_e32 v2, 0x60, v0
	v_bitop3_b32 v2, v2, v82, v83 bitop3:0xde
	v_add_u32_e32 v143, 0, v2
	ds_read_b128 v[2:5], v143 offset:16384
	ds_read_b128 v[82:85], v143 offset:24576
	v_readlane_b32 s47, v252, 11
	v_readlane_b32 s48, v252, 12
	s_waitcnt lgkmcnt(2)
	v_mfma_f32_32x32x16_bf16 v[18:33], v[6:9], v[66:69], v[18:33]
	v_readlane_b32 s49, v252, 13
	v_readlane_b32 s50, v252, 14
	v_readlane_b32 s51, v252, 15
	v_add_u32_e32 v137, s9, v135
	v_writelane_b32 v252, s0, 0
	s_mov_b32 s76, s37
	s_mov_b32 s77, s37
	s_waitcnt lgkmcnt(1)
	v_mfma_f32_32x32x16_bf16 v[34:49], v[2:5], v[74:77], v[34:49]
	v_writelane_b32 v252, s1, 1
	v_writelane_b32 v252, s2, 2
	v_writelane_b32 v252, s3, 3
	v_writelane_b32 v252, s4, 4
	v_writelane_b32 v252, s5, 5
	v_writelane_b32 v252, s6, 6
	v_writelane_b32 v252, s7, 7
	s_waitcnt lgkmcnt(0)
	v_mfma_f32_32x32x16_bf16 v[18:33], v[82:85], v[74:77], v[18:33]
	s_nop 2
	v_max_f32_e32 v82, v35, v35
	v_max_f32_e32 v83, v34, v34
	v_max_f32_e32 v82, v83, v82
	v_max3_f32 v82, v82, v36, v37
	v_max3_f32 v82, v82, v38, v39
	v_max3_f32 v82, v82, v40, v41
	v_max3_f32 v82, v82, v42, v43
	v_max3_f32 v82, v82, v44, v45
	v_max3_f32 v82, v82, v46, v47
	v_max3_f32 v82, v82, v48, v49
	v_max3_f32 v82, v82, v18, v19
	v_max3_f32 v82, v82, v20, v21
	v_max3_f32 v82, v82, v22, v23
	v_max3_f32 v82, v82, v24, v25
	v_writelane_b32 v252, s8, 8
	v_max3_f32 v82, v82, v26, v27
	v_writelane_b32 v252, s9, 9
	v_max3_f32 v82, v82, v28, v29
	v_writelane_b32 v252, s10, 10
	v_max3_f32 v82, v82, v30, v31
	v_writelane_b32 v252, s11, 11
	v_max3_f32 v82, v82, v32, v33
	v_writelane_b32 v252, s12, 12
	v_mov_b32_e32 v83, v82
	v_writelane_b32 v252, s13, 13
	s_nop 0
	v_permlane32_swap_b32_e32 v82, v83
	v_writelane_b32 v252, s14, 14
	v_max_f32_e32 v95, v82, v82
	v_add_u32_e32 v82, 0xa0, v92
	v_writelane_b32 v252, s15, 15
	v_max_f32_e32 v94, v83, v83
	v_mad_i64_i32 v[82:83], s[0:1], v82, s95, v[50:51]
	v_lshl_add_u64 v[82:83], v[82:83], 0, v[90:91]
	global_load_dwordx4 v[86:89], v[82:83], off offset:3392
	v_add_u32_e32 v82, 0x80, v92
	v_mad_i64_i32 v[82:83], s[0:1], v82, s95, v[50:51]
	v_add_u32_e32 v84, 0x80, v93
	v_lshl_add_u64 v[82:83], v[82:83], 0, v[90:91]
	v_mad_i64_i32 v[50:51], s[0:1], v84, s95, v[50:51]
	v_lshl_add_u64 v[50:51], v[50:51], 0, v[52:53]
	global_load_dwordx4 v[90:93], v[82:83], off offset:3392
	s_nop 0
	global_load_dwordx4 v[82:85], v[50:51], off offset:3648
	v_max_f32_e32 v50, v95, v94
	v_add_f32_e32 v51, 0x7149f2ca, v50
	v_cmp_ge_f32_e32 vcc, s97, v51
	s_cmp_eq_u64 vcc, exec
	v_max_f32_e32 v51, 0xf149f2ca, v50
	s_cselect_b64 vcc, -1, 0
	v_mov_b32_e32 v50, 0xf149f2ca
	v_cndmask_b32_e32 v110, v51, v50, vcc
	v_mul_f32_e32 v50, 0xbe38aa3b, v110
	v_fmamk_f32 v34, v34, 0x3e38aa3b, v50
	v_exp_f32_e32 v120, v34
	v_fmamk_f32 v34, v35, 0x3e38aa3b, v50
	v_exp_f32_e32 v128, v34
	v_fmamk_f32 v34, v36, 0x3e38aa3b, v50
	v_exp_f32_e32 v121, v34
	v_fmamk_f32 v34, v37, 0x3e38aa3b, v50
	v_exp_f32_e32 v129, v34
	v_fmamk_f32 v34, v38, 0x3e38aa3b, v50
	v_exp_f32_e32 v126, v34
	v_fmamk_f32 v34, v39, 0x3e38aa3b, v50
	v_exp_f32_e32 v149, v34
	v_fmamk_f32 v34, v40, 0x3e38aa3b, v50
	v_exp_f32_e32 v127, v34
	v_fmamk_f32 v34, v41, 0x3e38aa3b, v50
	v_exp_f32_e32 v150, v34
	v_fmamk_f32 v34, v42, 0x3e38aa3b, v50
	v_exp_f32_e32 v112, v34
	v_fmamk_f32 v34, v43, 0x3e38aa3b, v50
	v_exp_f32_e32 v115, v34
	v_fmamk_f32 v34, v44, 0x3e38aa3b, v50
	v_exp_f32_e32 v113, v34
	v_fmamk_f32 v34, v45, 0x3e38aa3b, v50
	v_exp_f32_e32 v116, v34
	v_fmamk_f32 v34, v46, 0x3e38aa3b, v50
	v_exp_f32_e32 v114, v34
	v_fmamk_f32 v34, v47, 0x3e38aa3b, v50
	v_sub_f32_e32 v35, 0xf149f2ca, v51
	v_pk_fma_f32 v[102:103], v[22:23], s[94:95], v[50:51] op_sel_hi:[1,0,0]
	v_pk_fma_f32 v[106:107], v[20:21], s[94:95], v[50:51] op_sel_hi:[1,0,0]
	v_mov_b32_e32 v22, 0x894000
	v_and_b32_e32 v20, 15, v111
	s_mov_b32 s78, s37
	s_mov_b32 s79, s37
	s_mov_b32 s80, s37
	s_mov_b32 s81, s37
	s_mov_b32 s82, s37
	s_mov_b32 s83, s37
	s_mov_b32 s84, s37
	s_mov_b32 s85, s37
	s_mov_b32 s86, s37
	s_mov_b32 s87, s37
	s_mov_b32 s88, s37
	s_mov_b32 s89, s37
	s_mov_b32 s90, s37
	v_exp_f32_e32 v117, v34
	v_fmamk_f32 v34, v48, 0x3e38aa3b, v50
	v_mul_f32_e32 v35, 0x3e38aa3b, v35
	v_pk_fma_f32 v[108:109], v[18:19], s[94:95], v[50:51] op_sel_hi:[1,0,0]
	v_mad_u64_u32 v[18:19], s[10:11], s8, v22, v[122:123]
	v_lshlrev_b32_e32 v20, 4, v20
	v_mov_b32_e32 v21, v1
	v_readlane_b32 s36, v252, 18
	v_exp_f32_e32 v35, v35
	v_exp_f32_e32 v118, v34
	v_fmamk_f32 v34, v49, 0x3e38aa3b, v50
	s_addk_i32 s9, 0x2000
	v_lshl_add_u64 v[18:19], v[18:19], 0, v[20:21]
	v_readlane_b32 s40, v252, 22
	v_readlane_b32 s41, v252, 23
	v_and_b32_e32 v20, 7, v111
	s_mov_b32 s91, s13
	v_mov_b64_e32 v[2:3], s[76:77]
	v_exp_f32_e32 v119, v34
	v_add_u32_e32 v135, s9, v135
	v_lshl_add_u64 v[122:123], s[40:41], 0, v[18:19]
	v_mad_u64_u32 v[18:19], s[8:9], s8, v22, v[124:125]
	v_lshlrev_b32_e32 v20, 4, v20
	v_mov_b64_e32 v[16:17], s[90:91]
	s_waitcnt vmcnt(3)
	v_lshl_add_u64 v[18:19], v[18:19], 0, v[20:21]
	v_mov_b64_e32 v[4:5], s[78:79]
	v_mov_b64_e32 v[6:7], s[80:81]
	v_mov_b64_e32 v[8:9], s[82:83]
	v_mov_b64_e32 v[10:11], s[84:85]
	v_mov_b64_e32 v[12:13], s[86:87]
	v_mov_b64_e32 v[14:15], s[88:89]
	v_readlane_b32 s80, v254, 55
	v_pk_fma_f32 v[94:95], v[32:33], s[94:95], v[50:51] op_sel_hi:[1,0,0]
	v_pk_fma_f32 v[100:101], v[30:31], s[94:95], v[50:51] op_sel_hi:[1,0,0]
	v_pk_fma_f32 v[104:105], v[28:29], s[94:95], v[50:51] op_sel_hi:[1,0,0]
	v_pk_fma_f32 v[96:97], v[26:27], s[94:95], v[50:51] op_sel_hi:[1,0,0]
	v_pk_fma_f32 v[98:99], v[24:25], s[94:95], v[50:51] op_sel_hi:[1,0,0]
	v_lshl_add_u64 v[124:125], s[40:41], 0, v[18:19]
	v_mov_b64_e32 v[32:33], v[16:17]
	v_readlane_b32 s90, v254, 49
	v_readlane_b32 s78, v254, 53
	s_mov_b32 s19, 4
	v_readlane_b32 s81, v254, 56
	v_cndmask_b32_e64 v145, v35, 1.0, vcc
	v_cmp_gt_u32_e64 s[0:1], 32, v134
	v_lshl_add_u32 v134, v131, 2, v133
	v_mov_b32_e32 v136, 0
	v_mov_b64_e32 v[30:31], v[14:15]
	v_mov_b64_e32 v[28:29], v[12:13]
	v_mov_b64_e32 v[26:27], v[10:11]
	v_mov_b64_e32 v[24:25], v[8:9]
	v_mov_b64_e32 v[22:23], v[6:7]
	v_mov_b64_e32 v[20:21], v[4:5]
	v_mov_b64_e32 v[18:19], v[2:3]
	v_readlane_b32 s91, v254, 50
	v_readlane_b32 s79, v254, 54
	s_mov_b64 s[24:25], 0x7a000
	s_waitcnt vmcnt(5)
	ds_write_b128 v141, v[54:57] offset:8192
	s_waitcnt vmcnt(4)
	ds_write_b128 v139, v[58:61] offset:32768
	s_waitcnt vmcnt(3)
	ds_write_b128 v140, v[62:65] offset:32768
	s_waitcnt lgkmcnt(0)
	v_readlane_b32 s37, v252, 19
	v_readlane_b32 s38, v252, 20
	v_readlane_b32 s39, v252, 21
	v_readlane_b32 s42, v252, 24
	v_readlane_b32 s43, v252, 25
.Lrotgqa_head:
	s_barrier
.LBB0_692:
	ds_read_b128 v[34:37], v138 offset:32768
	ds_read_b128 v[38:41], v138 offset:40960
	ds_read_b128 v[152:155], v142 offset:32768
	ds_read_b128 v[156:159], v142 offset:40960
	v_exp_f32_e32 v151, v106
	v_add_f32_e32 v106, 0, v120
	s_waitcnt lgkmcnt(3)
	v_mfma_f32_32x32x16_bf16 v[50:65], v[34:37], v[78:81], 0
	v_add_f32_e32 v106, v128, v106
	v_add_f32_e32 v106, v121, v106
	v_add_f32_e32 v106, v129, v106
	v_add_f32_e32 v106, v126, v106
	v_add_f32_e32 v106, v149, v106
	v_add_f32_e32 v106, v127, v106
	v_add_f32_e32 v106, v150, v106
	s_waitcnt lgkmcnt(2)
	v_mfma_f32_32x32x16_bf16 v[34:49], v[38:41], v[78:81], 0
	v_add_f32_e32 v106, v112, v106
	v_add_f32_e32 v106, v115, v106
	v_add_f32_e32 v106, v113, v106
	v_add_f32_e32 v106, v116, v106
	v_exp_f32_e32 v111, v108
	v_add_f32_e32 v106, v114, v106
	v_exp_f32_e32 v148, v109
	s_waitcnt lgkmcnt(1)
	v_mfma_f32_32x32x16_bf16 v[50:65], v[152:155], v[70:73], v[50:65]
	v_add_f32_e32 v106, v117, v106
	v_add_f32_e32 v106, v118, v106
	v_add_f32_e32 v106, v119, v106
	v_exp_f32_e32 v102, v102
	v_add_f32_e32 v106, v111, v106
	v_exp_f32_e32 v103, v103
	v_add_f32_e32 v106, v148, v106
	s_waitcnt lgkmcnt(0)
	v_mfma_f32_32x32x16_bf16 v[34:49], v[156:159], v[70:73], v[34:49]
	ds_read_b128 v[152:155], v144 offset:32768
	ds_read_b128 v[156:159], v144 offset:40960
	v_exp_f32_e32 v98, v98
	v_add_f32_e32 v106, v151, v106
	v_exp_f32_e32 v99, v99
	v_exp_f32_e32 v96, v96
	v_exp_f32_e32 v97, v97
	v_exp_f32_e32 v104, v104
	s_waitcnt lgkmcnt(1)
	v_mfma_f32_32x32x16_bf16 v[50:65], v[152:155], v[66:69], v[50:65]
	v_exp_f32_e32 v105, v105
	v_exp_f32_e32 v100, v100
	v_exp_f32_e32 v101, v101
	v_exp_f32_e32 v94, v94
	v_exp_f32_e32 v95, v95
	s_waitcnt lgkmcnt(0)
	v_mfma_f32_32x32x16_bf16 v[34:49], v[156:159], v[66:69], v[34:49]
	ds_read_b128 v[152:155], v143 offset:32768
	ds_read_b128 v[156:159], v143 offset:40960
	s_waitcnt lgkmcnt(1)
	v_mfma_f32_32x32x16_bf16 v[50:65], v[152:155], v[74:77], v[50:65]
	v_exp_f32_e32 v152, v107
	s_nop 0
	v_add_f32_e32 v106, v152, v106
	v_add_f32_e32 v106, v102, v106
	v_add_f32_e32 v106, v103, v106
	v_add_f32_e32 v106, v98, v106
	v_add_f32_e32 v106, v99, v106
	v_add_f32_e32 v106, v96, v106
	v_add_f32_e32 v106, v97, v106
	s_waitcnt lgkmcnt(0)
	v_mfma_f32_32x32x16_bf16 v[34:49], v[156:159], v[74:77], v[34:49]
	v_add_f32_e32 v106, v104, v106
	v_add_f32_e32 v106, v105, v106
	v_add_f32_e32 v106, v100, v106
	v_add_f32_e32 v106, v101, v106
	v_add_f32_e32 v106, v94, v106
	v_add_f32_e32 v146, v95, v106
	v_mov_b32_e32 v147, v146
	v_cvt_pk_bf16_f32 v106, v120, v128
	v_cvt_pk_bf16_f32 v107, v121, v129
	v_cvt_pk_bf16_f32 v108, v126, v149
	v_cvt_pk_bf16_f32 v109, v127, v150
	v_cvt_pk_bf16_f32 v112, v112, v115
	v_cvt_pk_bf16_f32 v113, v113, v116
	v_cvt_pk_bf16_f32 v114, v114, v117
	v_cvt_pk_bf16_f32 v115, v118, v119
	v_cvt_pk_bf16_f32 v116, v111, v148
	v_cvt_pk_bf16_f32 v117, v151, v152
	v_cvt_pk_bf16_f32 v118, v102, v103
	v_cvt_pk_bf16_f32 v119, v98, v99
	v_cvt_pk_bf16_f32 v148, v96, v97
	v_cvt_pk_bf16_f32 v149, v104, v105
	v_cvt_pk_bf16_f32 v150, v100, v101
	s_nop 1
	v_permlane32_swap_b32_e32 v146, v147
	v_permlane32_swap_b32_e32 v106, v108
	v_cvt_pk_bf16_f32 v151, v94, v95
	v_permlane32_swap_b32_e32 v148, v150
	v_permlane32_swap_b32_e32 v107, v109
	v_permlane32_swap_b32_e32 v112, v114
	v_permlane32_swap_b32_e32 v113, v115
	v_permlane32_swap_b32_e32 v116, v118
	v_permlane32_swap_b32_e32 v117, v119
	v_permlane32_swap_b32_e32 v149, v151
	v_readlane_b32 s36, v252, 0
	v_readlane_b32 s37, v252, 1
	s_mov_b64 s[8:9], s[36:37]
	v_lshl_add_u64 v[128:129], v[124:125], 0, s[8:9]
	v_add_co_u32_e32 v94, vcc, s53, v128
	v_lshl_add_u64 v[126:127], v[122:123], 0, s[8:9]
	s_nop 0
	v_addc_co_u32_e32 v95, vcc, 0, v129, vcc
	v_add_co_u32_e32 v98, vcc, s53, v126
	s_mov_b32 s8, 0x1ed67000
	s_nop 0
	v_addc_co_u32_e32 v99, vcc, 0, v127, vcc
	v_add_co_u32_e32 v102, vcc, s8, v126
	global_load_dwordx4 v[94:97], v[94:95], off offset:1088
	s_nop 0
	v_addc_co_u32_e32 v103, vcc, 0, v127, vcc
	global_load_dwordx4 v[98:101], v[98:99], off offset:832
	s_nop 0
	global_load_dwordx4 v[102:105], v[102:103], off offset:2880
	v_readlane_b32 s38, v252, 2
	v_readlane_b32 s39, v252, 3
	v_readlane_b32 s40, v252, 4
	v_readlane_b32 s41, v252, 5
	v_readlane_b32 s42, v252, 6
	v_readlane_b32 s43, v252, 7
	v_readlane_b32 s44, v252, 8
	v_readlane_b32 s45, v252, 9
	v_readlane_b32 s46, v252, 10
	v_readlane_b32 s47, v252, 11
	v_readlane_b32 s48, v252, 12
	v_readlane_b32 s49, v252, 13
	v_readlane_b32 s50, v252, 14
	v_readlane_b32 s51, v252, 15
	ds_read_b64_tr_b16 v[152:153], v137 offset:0
	ds_read_b64_tr_b16 v[154:155], v137 offset:0x400
	ds_read_b64_tr_b16 v[156:157], v137 offset:0x800
	ds_read_b64_tr_b16 v[158:159], v137 offset:0xc00
	ds_read_b64_tr_b16 v[160:161], v137 offset:0x1000
	ds_read_b64_tr_b16 v[162:163], v137 offset:0x1400
	ds_read_b64_tr_b16 v[164:165], v137 offset:0x1800
	ds_read_b64_tr_b16 v[166:167], v137 offset:0x1c00
	s_waitcnt lgkmcnt(0)
	s_nop 0
	v_mfma_f32_32x32x16_bf16 v[2:17], v[106:109], v[152:155], v[2:17]
	ds_read_b64_tr_b16 v[152:153], v137 offset:0x200
	ds_read_b64_tr_b16 v[154:155], v137 offset:0x600
	v_mfma_f32_32x32x16_bf16 v[2:17], v[112:115], v[156:159], v[2:17]
	ds_read_b64_tr_b16 v[156:157], v137 offset:0xa00
	ds_read_b64_tr_b16 v[158:159], v137 offset:0xe00
	v_mfma_f32_32x32x16_bf16 v[2:17], v[116:119], v[160:163], v[2:17]
	ds_read_b64_tr_b16 v[160:161], v137 offset:0x1200
	ds_read_b64_tr_b16 v[162:163], v137 offset:0x1600
	v_mfma_f32_32x32x16_bf16 v[2:17], v[148:151], v[164:167], v[2:17]
	ds_read_b64_tr_b16 v[164:165], v137 offset:0x1a00
	ds_read_b64_tr_b16 v[166:167], v137 offset:0x1e00
	s_waitcnt lgkmcnt(0)
	v_mfma_f32_32x32x16_bf16 v[18:33], v[106:109], v[152:155], v[18:33]
	v_max_f32_e32 v106, v51, v51
	v_max_f32_e32 v107, v50, v50
	v_max_f32_e32 v106, v107, v106
	v_max3_f32 v106, v106, v52, v53
	v_max3_f32 v106, v106, v54, v55
	v_max3_f32 v106, v106, v56, v57
	v_max3_f32 v106, v106, v58, v59
	v_max3_f32 v106, v106, v60, v61
	v_max3_f32 v106, v106, v62, v63
	v_mfma_f32_32x32x16_bf16 v[18:33], v[112:115], v[156:159], v[18:33]
	v_max3_f32 v106, v106, v64, v65
	v_max3_f32 v106, v106, v34, v35
	v_max3_f32 v106, v106, v36, v37
	v_max3_f32 v106, v106, v38, v39
	v_max3_f32 v106, v106, v40, v41
	v_max3_f32 v106, v106, v42, v43
	v_max3_f32 v106, v106, v44, v45
	v_max3_f32 v106, v106, v46, v47
	v_mfma_f32_32x32x16_bf16 v[18:33], v[116:119], v[160:163], v[18:33]
	v_max3_f32 v106, v106, v48, v49
	v_mov_b32_e32 v107, v106
	s_nop 1
	v_permlane32_swap_b32_e32 v106, v107
	v_max_f32_e32 v107, v107, v107
	v_max_f32_e32 v106, v106, v106
	v_max_f32_e32 v106, v106, v107
	v_sub_f32_e32 v107, v106, v110
	v_cmp_ge_f32_e32 vcc, s97, v107
	v_max_f32_e32 v107, v110, v110
	v_max_f32_e32 v106, v107, v106
	v_mfma_f32_32x32x16_bf16 v[18:33], v[148:151], v[164:167], v[18:33]
	v_sub_f32_e32 v107, v110, v106
	v_mul_f32_e32 v107, 0x3e38aa3b, v107
	v_exp_f32_e32 v107, v107
	s_cmp_eq_u64 vcc, exec
	s_cselect_b64 s[8:9], -1, 0
	s_barrier
	s_waitcnt vmcnt(3)
	v_cndmask_b32_e64 v148, v107, 1.0, s[8:9]
	v_cmp_gt_f32_e32 vcc, 1.0, v148
	s_waitcnt vmcnt(3)
	ds_write_b128 v141, v[82:85]
	ds_write_b128 v139, v[90:93] offset:16384
	ds_write_b128 v140, v[86:89] offset:16384
	s_cbranch_vccz .LBB0_696
	s_and_saveexec_b64 s[10:11], s[0:1]
	ds_write_b32 v134, v148 offset:49280
	s_or_b64 exec, exec, s[10:11]
	s_waitcnt lgkmcnt(0)
	v_add_u32_e32 v107, v133, v0
	ds_read_b128 v[112:115], v107 offset:49376
	ds_read_b128 v[116:119], v107 offset:49344
	ds_read_b128 v[150:153], v107 offset:49312
	ds_read_b128 v[154:157], v107 offset:49280
	s_waitcnt lgkmcnt(3)
	v_pk_mul_f32 v[14:15], v[14:15], v[112:113]
	s_waitcnt lgkmcnt(2)
	v_pk_mul_f32 v[10:11], v[10:11], v[116:117]
	s_waitcnt lgkmcnt(1)
	v_pk_mul_f32 v[6:7], v[6:7], v[150:151]
	v_pk_mul_f32 v[16:17], v[16:17], v[114:115]
	v_pk_mul_f32 v[12:13], v[12:13], v[118:119]
	v_pk_mul_f32 v[8:9], v[8:9], v[152:153]
	s_waitcnt lgkmcnt(0)
	v_pk_mul_f32 v[4:5], v[4:5], v[156:157]
	v_pk_mul_f32 v[2:3], v[2:3], v[154:155]
	v_pk_mul_f32 v[30:31], v[30:31], v[112:113]
	v_pk_mul_f32 v[26:27], v[26:27], v[116:117]
	v_pk_mul_f32 v[22:23], v[22:23], v[150:151]
	v_pk_mul_f32 v[32:33], v[32:33], v[114:115]
	v_pk_mul_f32 v[28:29], v[28:29], v[118:119]
	v_pk_mul_f32 v[24:25], v[24:25], v[152:153]
	v_pk_mul_f32 v[20:21], v[20:21], v[156:157]
	v_pk_mul_f32 v[18:19], v[18:19], v[154:155]

.LBB0_702:
	v_cndmask_b32_e64 v110, v106, v149, s[8:9]
	v_mul_f32_e32 v94, 0xbe38aa3b, v110
	v_pk_fma_f32 v[50:51], v[50:51], s[94:95], v[94:95] op_sel_hi:[1,0,0]
	v_pk_fma_f32 v[52:53], v[52:53], s[94:95], v[94:95] op_sel_hi:[1,0,0]
	v_pk_fma_f32 v[54:55], v[54:55], s[94:95], v[94:95] op_sel_hi:[1,0,0]
	v_pk_fma_f32 v[56:57], v[56:57], s[94:95], v[94:95] op_sel_hi:[1,0,0]
	v_pk_fma_f32 v[58:59], v[58:59], s[94:95], v[94:95] op_sel_hi:[1,0,0]
	v_pk_fma_f32 v[60:61], v[60:61], s[94:95], v[94:95] op_sel_hi:[1,0,0]
	v_pk_fma_f32 v[62:63], v[62:63], s[94:95], v[94:95] op_sel_hi:[1,0,0]
	v_pk_fma_f32 v[64:65], v[64:65], s[94:95], v[94:95] op_sel_hi:[1,0,0]
	v_exp_f32_e32 v120, v50
	v_exp_f32_e32 v128, v51
	v_exp_f32_e32 v121, v52
	v_exp_f32_e32 v129, v53
	v_exp_f32_e32 v126, v54
	v_exp_f32_e32 v149, v55
	v_exp_f32_e32 v127, v56
	v_exp_f32_e32 v150, v57
	v_exp_f32_e32 v112, v58
	v_exp_f32_e32 v115, v59
	v_exp_f32_e32 v113, v60
	v_exp_f32_e32 v116, v61
	v_exp_f32_e32 v114, v62
	v_exp_f32_e32 v117, v63
	v_exp_f32_e32 v118, v64
	v_exp_f32_e32 v119, v65
	v_pk_fma_f32 v[108:109], v[34:35], s[94:95], v[94:95] op_sel_hi:[1,0,0]
	v_add_f32_e32 v34, v146, v147
	v_fmac_f32_e32 v34, v145, v136
	v_add_f32_e32 v136, v151, v152
	v_pk_fma_f32 v[106:107], v[36:37], s[94:95], v[94:95] op_sel_hi:[1,0,0]
	v_pk_fma_f32 v[102:103], v[38:39], s[94:95], v[94:95] op_sel_hi:[1,0,0]
	v_pk_fma_f32 v[98:99], v[40:41], s[94:95], v[94:95] op_sel_hi:[1,0,0]
	v_pk_fma_f32 v[96:97], v[42:43], s[94:95], v[94:95] op_sel_hi:[1,0,0]
	v_pk_fma_f32 v[104:105], v[44:45], s[94:95], v[94:95] op_sel_hi:[1,0,0]
	v_pk_fma_f32 v[100:101], v[46:47], s[94:95], v[94:95] op_sel_hi:[1,0,0]
	v_pk_fma_f32 v[94:95], v[48:49], s[94:95], v[94:95] op_sel_hi:[1,0,0]
	v_fmac_f32_e32 v136, v34, v148
	v_lshl_add_u64 v[122:123], v[122:123], 0, s[24:25]
	v_lshl_add_u64 v[124:125], v[124:125], 0, s[24:25]
	s_add_i32 s19, s19, 2
	s_and_b64 vcc, exec, s[10:11]
	s_waitcnt lgkmcnt(0)
	s_cbranch_vccnz .Lrotgqa_exit
	v_mov_b32_e32 v145, v111
	s_branch .Lrotgqa_head
.Lrotgqa_exit:
	s_barrier
	s_branch .LBB0_783

.LBB0_917:
	s_and_b32 s9, s11, 3
	s_add_i32 s12, s16, 0x100
	s_and_b64 s[6:7], exec, s[6:7]
	s_mul_i32 s11, s10, 0x900
	s_cselect_b32 s6, 0, s12
	s_mul_hi_i32 s8, s10, 0x900
	s_add_u32 s6, s11, s6
	s_addc_u32 s7, s8, 0
	s_lshl_b64 s[6:7], s[6:7], 11
	s_add_u32 s6, s74, s6
	s_addc_u32 s7, s75, s7
	s_mul_i32 s8, s9, 0xc0
	s_add_u32 s6, s6, s8
	s_addc_u32 s7, s7, 0
	s_mul_i32 s14, s10, 0x480000
	s_mul_hi_i32 s15, s10, 0x480000
	s_add_u32 s12, s74, s14
	s_addc_u32 s13, s75, s15
	s_add_u32 s10, s12, s8
	s_addc_u32 s11, s13, 0
	s_lshl_b32 s9, s9, 7
	s_add_u32 s12, s12, s9
	s_addc_u32 s13, s13, 0
	s_andn2_b64 vcc, exec, s[0:1]
	s_mov_b64 s[0:1], -1
	s_cbranch_vccnz .LBB0_939
	s_waitcnt vmcnt(2)
	v_mov_b32_e32 v58, v211
	s_movk_i32 s0, 0xffe0
	v_ashrrev_i32_e32 v12, 1, v58
	v_bfi_b32 v2, s0, v12, v58
	v_ashrrev_i32_e32 v3, 31, v2
	v_bfe_u32 v140, v58, 5, 1
	v_lshlrev_b64 v[2:3], 11, v[2:3]
	v_lshl_add_u64 v[2:3], s[6:7], 0, v[2:3]
	v_lshlrev_b32_e32 v0, 4, v140
	v_lshl_add_u64 v[10:11], v[2:3], 0, v[0:1]
	global_load_dwordx4 v[2:5], v[10:11], off offset:160
	global_load_dwordx4 v[6:9], v[10:11], off offset:128
	v_and_b32_e32 v141, 31, v58
	v_and_b32_e32 v130, 0xffffffe0, v12
	v_or_b32_e32 v12, s16, v141
	v_add_u32_e32 v12, v12, v130
	v_and_b32_e32 v13, 63, v12
	v_ashrrev_i32_e32 v12, 6, v12
	v_cvt_f32_i32_e32 v12, v12
	v_and_b32_e32 v59, 63, v58
	v_cvt_f32_ubyte0_e32 v13, v13
	v_cmp_gt_u32_e64 s[0:1], 32, v59
	global_load_dwordx4 v[78:81], v[10:11], off
	global_load_dwordx4 v[74:77], v[10:11], off offset:32
	global_load_dwordx4 v[70:73], v[10:11], off offset:64
	global_load_dwordx4 v[66:69], v[10:11], off offset:96
	v_cndmask_b32_e64 v38, v13, v12, s[0:1]
	v_mul_f32_e32 v13, 0x3dcccccd, v38
	v_mul_f32_e32 v14, 0x3d0186e3, v38
	v_mul_f32_e32 v12, 0x3ea1e89b, v38
	v_mul_f32_e32 v15, 0x3c23d70b, v38
	v_mul_f32_e32 v16, 0x3b4f3e39, v38
	v_mul_f32_e32 v17, 0.15915494, v13
	s_waitcnt vmcnt(7)
	v_mul_f32_e32 v18, 0.15915494, v14
	v_mul_f32_e32 v10, 0.15915494, v38
	v_mul_f32_e32 v12, 0.15915494, v12
	v_mul_f32_e32 v20, 0.15915494, v15
	s_waitcnt vmcnt(6)
	v_mul_f32_e32 v22, 0.15915494, v16
	v_sin_f32_e32 v15, v17
	v_cos_f32_e32 v14, v17
	v_sin_f32_e32 v17, v18
	v_cos_f32_e32 v16, v18
	v_sin_f32_e32 v11, v10
	v_cos_f32_e32 v10, v10
	v_sin_f32_e32 v13, v12
	v_cos_f32_e32 v12, v12
	v_sin_f32_e32 v19, v20
	v_cos_f32_e32 v18, v20
	v_mov_b32_e32 v28, v17
	v_mov_b32_e32 v29, v16
	v_sin_f32_e32 v21, v22
	v_cos_f32_e32 v20, v22
	v_mov_b32_e32 v22, v11
	v_mov_b32_e32 v23, v10
	v_mov_b32_e32 v24, v13
	v_mov_b32_e32 v25, v12
	v_mov_b32_e32 v26, v15
	v_mov_b32_e32 v27, v14
	v_mov_b32_e32 v30, v19
	v_mov_b32_e32 v31, v18
	v_lshlrev_b32_e32 v60, 4, v58
	v_readlane_b32 s36, v252, 0
	s_cmp_lg_u32 0, -1
	v_readlane_b32 s37, v252, 1
	s_cselect_b32 s16, 0, 0
	s_mov_b32 s5, s37
	v_readlane_b32 s38, v252, 2
	v_readlane_b32 s39, v252, 3
	v_readlane_b32 s40, v252, 4
	v_readlane_b32 s41, v252, 5
	v_readlane_b32 s42, v252, 6
	v_readlane_b32 s43, v252, 7
	v_readlane_b32 s44, v252, 8
	v_readlane_b32 s45, v252, 9
	v_readlane_b32 s46, v252, 10
	v_readlane_b32 s47, v252, 11
	v_readlane_b32 s48, v252, 12
	v_readlane_b32 s49, v252, 13
	v_readlane_b32 s50, v252, 14
	v_readlane_b32 s51, v252, 15
	s_mov_b32 s36, s37
	s_mov_b32 s38, s37
	s_mov_b32 s39, s37
	s_mov_b32 s40, s37
	s_mov_b32 s41, s37
	s_mov_b32 s42, s37
	s_mov_b32 s43, s37
	s_mov_b32 s44, s37
	s_mov_b32 s45, s37
	s_mov_b32 s46, s37
	s_mov_b32 s47, s37
	s_mov_b32 s48, s37
	s_mov_b32 s49, s37
	s_waitcnt vmcnt(5)
	v_lshlrev_b32_e32 v33, 16, v2
	v_and_b32_e32 v35, 0xffff0000, v2
	v_lshlrev_b32_e32 v37, 16, v3
	v_and_b32_e32 v3, 0xffff0000, v3
	s_waitcnt vmcnt(4)
	v_and_b32_e32 v2, 0xffff0000, v7
	v_lshlrev_b32_e32 v32, 16, v6
	v_and_b32_e32 v34, 0xffff0000, v6
	v_lshlrev_b32_e32 v36, 16, v7
	v_pk_mul_f32 v[16:17], v[16:17], v[2:3]
	v_pk_mul_f32 v[2:3], v[28:29], v[2:3]
	v_lshlrev_b32_e32 v7, 16, v4
	v_lshlrev_b32_e32 v6, 16, v8
	v_pk_mul_f32 v[10:11], v[10:11], v[32:33]
	v_pk_mul_f32 v[22:23], v[22:23], v[32:33]
	v_pk_mul_f32 v[12:13], v[12:13], v[34:35]
	v_pk_mul_f32 v[24:25], v[24:25], v[34:35]
	v_pk_mul_f32 v[14:15], v[14:15], v[36:37]
	v_pk_mul_f32 v[26:27], v[26:27], v[36:37]
	v_add_f32_e32 v2, v2, v3
	v_sub_f32_e32 v10, v10, v11
	v_add_f32_e32 v11, v22, v23
	v_sub_f32_e32 v12, v12, v13
	v_add_f32_e32 v13, v24, v25
	v_sub_f32_e32 v14, v14, v15
	v_add_f32_e32 v15, v26, v27
	v_sub_f32_e32 v16, v16, v17
	v_cvt_pk_bf16_f32 v86, v10, v12
	v_cvt_pk_bf16_f32 v82, v11, v13
	v_cvt_pk_bf16_f32 v87, v14, v16
	v_cvt_pk_bf16_f32 v83, v15, v2
	v_pk_mul_f32 v[2:3], v[30:31], v[6:7]
	v_pk_mul_f32 v[18:19], v[18:19], v[6:7]
	v_add_f32_e32 v10, v2, v3
	v_and_b32_e32 v3, 0xffff0000, v4
	v_and_b32_e32 v2, 0xffff0000, v8
	v_pk_mul_f32 v[6:7], v[20:21], v[2:3]
	v_sub_f32_e32 v17, v18, v19
	v_sub_f32_e32 v4, v6, v7
	v_mov_b32_e32 v6, v21
	v_mov_b32_e32 v7, v20
	v_pk_mul_f32 v[2:3], v[6:7], v[2:3]
	v_cvt_pk_bf16_f32 v88, v17, v4
	v_mul_f32_e32 v4, 0x39a5cb61, v38
	v_add_f32_e32 v2, v2, v3
	v_cvt_pk_bf16_f32 v84, v10, v2
	v_mul_f32_e32 v2, 0x3a831270, v38
	v_mul_f32_e32 v2, 0.15915494, v2
	v_sin_f32_e32 v3, v2
	v_cos_f32_e32 v2, v2
	v_mul_f32_e32 v4, 0.15915494, v4
	v_lshlrev_b32_e32 v11, 16, v5
	v_lshlrev_b32_e32 v10, 16, v9
	v_sin_f32_e32 v7, v4
	v_cos_f32_e32 v6, v4
	v_pk_mul_f32 v[12:13], v[2:3], v[10:11]
	v_ashrrev_i32_e32 v16, 3, v58
	v_sub_f32_e32 v8, v12, v13
	v_mov_b32_e32 v12, v3
	v_mov_b32_e32 v13, v2
	v_pk_mul_f32 v[2:3], v[12:13], v[10:11]
	v_ashrrev_i32_e32 v14, 4, v58
	v_add_f32_e32 v10, v2, v3
	v_and_b32_e32 v3, 0xffff0000, v5
	v_and_b32_e32 v2, 0xffff0000, v9
	v_pk_mul_f32 v[4:5], v[6:7], v[2:3]
	v_lshlrev_b32_e32 v22, 3, v58
	v_sub_f32_e32 v4, v4, v5
	v_cvt_pk_bf16_f32 v89, v8, v4
	v_mov_b32_e32 v4, v7
	v_mov_b32_e32 v5, v6
	v_pk_mul_f32 v[2:3], v[4:5], v[2:3]
	v_ashrrev_i32_e32 v17, 31, v16
	v_add_f32_e32 v2, v2, v3
	v_and_b32_e32 v4, 56, v22
	v_lshlrev_b64 v[50:51], 11, v[16:17]
	v_ashrrev_i32_e32 v15, 31, v14
	v_cvt_pk_bf16_f32 v85, v10, v2
	v_lshl_add_u64 v[2:3], s[12:13], 0, v[50:51]
	v_lshlrev_b32_e32 v4, 1, v4
	v_mov_b32_e32 v5, v1
	v_lshlrev_b64 v[52:53], 11, v[14:15]
	v_add_u32_e32 v20, 32, v14
	v_lshl_add_u64 v[54:55], v[2:3], 0, v[4:5]
	v_lshl_add_u64 v[2:3], s[10:11], 0, v[52:53]
	v_and_b32_e32 v18, 0xf0, v60
	v_mov_b32_e32 v19, v1
	v_ashrrev_i32_e32 v21, 31, v20
	v_lshl_add_u64 v[56:57], v[2:3], 0, v[18:19]
	global_load_dwordx4 v[2:5], v[54:55], off offset:1536
	global_load_dwordx4 v[6:9], v[56:57], off offset:768
	v_lshlrev_b64 v[10:11], 11, v[20:21]
	v_lshl_add_u64 v[10:11], s[10:11], 0, v[10:11]
	v_lshl_add_u64 v[10:11], v[10:11], 0, v[18:19]
	global_load_dwordx4 v[10:13], v[10:11], off offset:768
	v_and_b32_e32 v17, 0x1fffff0, v16
	v_lshlrev_b32_e32 v19, 1, v16
	v_lshrrev_b32_e32 v21, 1, v16
	v_and_b32_e32 v16, 3, v16
	v_and_or_b32 v17, v19, 8, v17
	v_bfe_u32 v22, v22, 5, 1
	v_and_b32_e32 v23, 48, v60
	v_and_or_b32 v16, v21, 4, v16
	v_lshrrev_b32_e32 v17, 2, v17
	v_lshl_or_b32 v16, v16, 6, v23
	v_or_b32_e32 v17, v17, v22
	v_lshl_or_b32 v16, v17, 9, v16
	v_and_b32_e32 v15, 0x70, v58
	v_lshlrev_b32_e32 v14, 8, v14
	v_add_u32_e32 v146, 0, v16
	s_waitcnt vmcnt(0)
	s_mov_b32 s50, s37
	s_mov_b32 s51, s37
	s_mov_b32 s24, 1
	v_mov_b32_e32 v144, 0
	s_waitcnt vmcnt(2)
	ds_write_b128 v146, v[2:5]
	v_bitop3_b32 v2, v18, v14, v15 bitop3:0xde
	v_add_u32_e32 v147, 0, v2
	v_lshlrev_b32_e32 v2, 8, v20
	v_bitop3_b32 v2, v18, v2, v15 bitop3:0xde
	v_add_u32_e32 v148, 0, v2
	s_waitcnt vmcnt(1)
	ds_write_b128 v147, v[6:9] offset:16384
	s_waitcnt vmcnt(0)
	ds_write_b128 v148, v[10:13] offset:16384
	v_lshlrev_b32_e32 v10, 8, v141
	v_and_b32_e32 v11, 0x70, v60
	v_bitop3_b32 v2, v0, v10, v11 bitop3:0xde
	v_add_u32_e32 v149, 0, v2
	s_waitcnt lgkmcnt(0)
	s_barrier
	ds_read_b128 v[2:5], v149 offset:16384
	ds_read_b128 v[6:9], v149 offset:24576
	s_waitcnt lgkmcnt(1)
	v_mfma_f32_32x32x16_bf16 v[34:49], v[2:5], v[78:81], 0
	v_or_b32_e32 v2, 32, v0
	v_bitop3_b32 v2, v2, v10, v11 bitop3:0xde
	v_add_u32_e32 v152, 0, v2
	v_and_b32_e32 v12, 0x3fffffc0, v58
	v_lshl_add_u32 v131, v12, 2, 0
	v_lshlrev_b32_e32 v12, 3, v59
	v_lshlrev_b32_e32 v14, 1, v58
	s_waitcnt lgkmcnt(0)
	v_mfma_f32_32x32x16_bf16 v[18:33], v[6:9], v[78:81], 0
	ds_read_b128 v[2:5], v152 offset:16384
	ds_read_b128 v[6:9], v152 offset:24576
	v_lshl_add_u32 v142, v141, 2, v131
	s_waitcnt lgkmcnt(1)
	v_mfma_f32_32x32x16_bf16 v[34:49], v[2:5], v[74:77], v[34:49]
	v_or_b32_e32 v2, 64, v0
	v_bitop3_b32 v2, v2, v10, v11 bitop3:0xde
	v_add_u32_e32 v151, 0, v2
	s_waitcnt lgkmcnt(0)
	v_mfma_f32_32x32x16_bf16 v[18:33], v[6:9], v[74:77], v[18:33]
	ds_read_b128 v[2:5], v151 offset:16384
	ds_read_b128 v[6:9], v151 offset:24576
	s_waitcnt lgkmcnt(1)
	v_mfma_f32_32x32x16_bf16 v[34:49], v[2:5], v[70:73], v[34:49]
	v_or_b32_e32 v2, 0x60, v0
	v_bitop3_b32 v2, v2, v10, v11 bitop3:0xde
	v_add_u32_e32 v150, 0, v2
	ds_read_b128 v[2:5], v150 offset:16384
	s_waitcnt lgkmcnt(1)
	v_mfma_f32_32x32x16_bf16 v[18:33], v[6:9], v[70:73], v[18:33]
	v_and_b32_e32 v6, 0xc0, v60
	v_and_or_b32 v13, v12, 24, v6
	ds_read_b128 v[6:9], v150 offset:24576
	s_waitcnt lgkmcnt(1)
	v_mfma_f32_32x32x16_bf16 v[34:49], v[2:5], v[66:69], v[34:49]
	v_or_b32_e32 v2, 0x80, v0
	v_bitop3_b32 v15, v2, v10, v11 bitop3:0xde
	v_add_co_u32_e32 v2, vcc, s52, v54
	v_add_u32_e32 v153, 0, v15
	s_nop 0
	v_addc_co_u32_e32 v3, vcc, 0, v55, vcc
	v_add_co_u32_e32 v4, vcc, s52, v56
	s_waitcnt lgkmcnt(0)
	v_mfma_f32_32x32x16_bf16 v[18:33], v[6:9], v[66:69], v[18:33]
	v_addc_co_u32_e32 v5, vcc, 0, v57, vcc
	global_load_dwordx4 v[60:63], v[2:3], off offset:1536
	global_load_dwordx4 v[102:105], v[4:5], off offset:768
	v_add_co_u32_e32 v2, vcc, s86, v56
	v_and_b32_e32 v6, 32, v14
	s_nop 0
	v_addc_co_u32_e32 v3, vcc, 0, v57, vcc
	global_load_dwordx4 v[106:109], v[2:3], off offset:768
	ds_read_b128 v[2:5], v153 offset:16384
	v_and_b32_e32 v7, 0x100, v12
	v_or3_b32 v59, v13, v6, v7
	ds_read_b128 v[6:9], v153 offset:24576
	s_waitcnt lgkmcnt(1)
	v_mfma_f32_32x32x16_bf16 v[34:49], v[2:5], v[86:89], v[34:49]
	v_or_b32_e32 v2, 0xa0, v0
	v_bitop3_b32 v2, v2, v10, v11 bitop3:0xde
	v_add_u32_e32 v154, 0, v2
	ds_read_b128 v[2:5], v154 offset:16384
	ds_read_b128 v[90:93], v154 offset:24576
	v_add_u32_e32 v145, s16, v59
	v_writelane_b32 v252, s4, 0
	s_waitcnt lgkmcnt(1)
	v_mfma_f32_32x32x16_bf16 v[34:49], v[2:5], v[82:85], v[34:49]
	v_writelane_b32 v252, s5, 1
	v_writelane_b32 v252, s6, 2
	v_writelane_b32 v252, s7, 3
	v_writelane_b32 v252, s8, 4
	v_writelane_b32 v252, s9, 5
	v_writelane_b32 v252, s10, 6
	v_writelane_b32 v252, s11, 7
	v_mfma_f32_32x32x16_bf16 v[18:33], v[6:9], v[86:89], v[18:33]
	s_nop 3
	v_max_f32_e32 v64, v35, v35
	v_max_f32_e32 v65, v34, v34
	v_max_f32_e32 v64, v65, v64
	v_max3_f32 v64, v64, v36, v37
	v_max3_f32 v64, v64, v38, v39
	v_max3_f32 v64, v64, v40, v41
	v_max3_f32 v64, v64, v42, v43
	s_waitcnt lgkmcnt(0)
	v_mfma_f32_32x32x16_bf16 v[18:33], v[90:93], v[82:85], v[18:33]
	v_max3_f32 v64, v64, v44, v45
	v_max3_f32 v64, v64, v46, v47
	v_writelane_b32 v252, s12, 8
	v_max3_f32 v64, v64, v48, v49
	v_writelane_b32 v252, s13, 9
	v_writelane_b32 v252, s14, 10
	v_writelane_b32 v252, s15, 11
	s_nop 4
	v_max3_f32 v64, v64, v18, v19
	v_max3_f32 v64, v64, v20, v21
	v_max3_f32 v64, v64, v22, v23
	v_writelane_b32 v252, s16, 12
	v_max3_f32 v64, v64, v24, v25
	v_writelane_b32 v252, s17, 13
	v_max3_f32 v64, v64, v26, v27
	v_writelane_b32 v252, s18, 14
	v_max3_f32 v64, v64, v28, v29
	v_writelane_b32 v252, s19, 15
	v_max3_f32 v64, v64, v30, v31
	s_mov_b32 s4, 0x50000
	v_max3_f32 v110, v64, v32, v33
	v_add_co_u32_e32 v64, vcc, s4, v56
	s_mov_b32 s4, 0x40000
	s_nop 0
	v_addc_co_u32_e32 v65, vcc, 0, v57, vcc
	v_add_co_u32_e32 v56, vcc, s4, v56
	global_load_dwordx4 v[94:97], v[64:65], off offset:768
	s_nop 0
	v_addc_co_u32_e32 v57, vcc, 0, v57, vcc
	v_add_co_u32_e32 v54, vcc, s4, v54
	v_mov_b64_e32 v[2:3], s[36:37]
	s_nop 0
	v_addc_co_u32_e32 v55, vcc, 0, v55, vcc
	global_load_dwordx4 v[98:101], v[56:57], off offset:768
	global_load_dwordx4 v[90:93], v[54:55], off offset:1536
	v_mov_b32_e32 v54, v110
	s_nop 1
	v_permlane32_swap_b32_e32 v110, v54
	v_max_f32_e32 v54, v54, v54
	v_max_f32_e32 v55, v110, v110
	v_max_f32_e32 v54, v55, v54
	v_add_f32_e32 v55, 0x7149f2ca, v54
	v_cmp_ge_f32_e32 vcc, s72, v55
	s_cmp_eq_u64 vcc, exec
	v_max_f32_e32 v55, 0xf149f2ca, v54
	s_cselect_b64 vcc, -1, 0
	v_mov_b32_e32 v54, 0xf149f2ca
	v_cndmask_b32_e32 v118, v55, v54, vcc
	v_mul_f32_e32 v54, 0xbe16c740, v118
	v_fmamk_f32 v34, v34, 0x3e16c740, v54
	v_exp_f32_e32 v128, v34
	v_fmamk_f32 v34, v35, 0x3e16c740, v54
	v_exp_f32_e32 v138, v34
	v_fmamk_f32 v34, v36, 0x3e16c740, v54
	v_exp_f32_e32 v129, v34
	v_fmamk_f32 v34, v37, 0x3e16c740, v54
	v_exp_f32_e32 v139, v34
	v_fmamk_f32 v34, v38, 0x3e16c740, v54
	v_exp_f32_e32 v136, v34
	v_fmamk_f32 v34, v39, 0x3e16c740, v54
	v_exp_f32_e32 v159, v34
	v_fmamk_f32 v34, v40, 0x3e16c740, v54
	v_exp_f32_e32 v137, v34
	v_fmamk_f32 v34, v41, 0x3e16c740, v54
	v_exp_f32_e32 v160, v34
	v_fmamk_f32 v34, v42, 0x3e16c740, v54
	v_exp_f32_e32 v120, v34
	v_fmamk_f32 v34, v43, 0x3e16c740, v54
	v_exp_f32_e32 v123, v34
	v_fmamk_f32 v34, v44, 0x3e16c740, v54
	v_exp_f32_e32 v121, v34
	v_fmamk_f32 v34, v45, 0x3e16c740, v54
	v_exp_f32_e32 v124, v34
	v_fmamk_f32 v34, v46, 0x3e16c740, v54
	v_exp_f32_e32 v122, v34
	v_fmamk_f32 v34, v47, 0x3e16c740, v54
	v_sub_f32_e32 v35, 0xf149f2ca, v55
	v_pk_fma_f32 v[116:117], v[18:19], s[96:97], v[54:55] op_sel_hi:[1,0,0]
	v_and_b32_e32 v18, 15, v58
	v_mov_b64_e32 v[4:5], s[38:39]
	v_mov_b64_e32 v[6:7], s[40:41]
	v_mov_b64_e32 v[8:9], s[42:43]
	v_mov_b64_e32 v[10:11], s[44:45]
	v_mov_b64_e32 v[12:13], s[46:47]
	v_mov_b64_e32 v[14:15], s[48:49]
	v_mov_b64_e32 v[16:17], s[50:51]
	v_exp_f32_e32 v125, v34
	v_fmamk_f32 v34, v48, 0x3e16c740, v54
	v_mul_f32_e32 v35, 0x3e16c740, v35
	v_or_b32_e32 v52, s8, v52
	v_lshlrev_b32_e32 v18, 4, v18
	v_mov_b32_e32 v19, v1
	v_readlane_b32 s36, v252, 18
	v_exp_f32_e32 v35, v35
	v_exp_f32_e32 v126, v34
	v_fmamk_f32 v34, v49, 0x3e16c740, v54
	v_lshl_add_u64 v[18:19], v[52:53], 0, v[18:19]
	v_readlane_b32 s40, v252, 22
	v_readlane_b32 s41, v252, 23
	v_exp_f32_e32 v127, v34
	s_waitcnt vmcnt(3)
	s_waitcnt vmcnt(5)
	ds_write_b128 v146, v[60:63] offset:8192
	s_waitcnt vmcnt(4)
	ds_write_b128 v147, v[102:105] offset:32768
	s_waitcnt vmcnt(3)
	ds_write_b128 v148, v[106:109] offset:32768
	v_lshl_add_u64 v[132:133], s[40:41], 0, v[18:19]
	v_and_b32_e32 v18, 7, v58
	v_lshlrev_b32_e32 v18, 4, v18
	v_pk_fma_f32 v[102:103], v[32:33], s[96:97], v[54:55] op_sel_hi:[1,0,0]
	v_pk_fma_f32 v[108:109], v[30:31], s[96:97], v[54:55] op_sel_hi:[1,0,0]
	v_pk_fma_f32 v[112:113], v[28:29], s[96:97], v[54:55] op_sel_hi:[1,0,0]
	v_pk_fma_f32 v[104:105], v[26:27], s[96:97], v[54:55] op_sel_hi:[1,0,0]
	v_pk_fma_f32 v[106:107], v[24:25], s[96:97], v[54:55] op_sel_hi:[1,0,0]
	v_pk_fma_f32 v[110:111], v[22:23], s[96:97], v[54:55] op_sel_hi:[1,0,0]
	v_pk_fma_f32 v[114:115], v[20:21], s[96:97], v[54:55] op_sel_hi:[1,0,0]
	s_addk_i32 s16, 0x2000
	v_or3_b32 v50, v50, s9, v18
	v_mov_b64_e32 v[32:33], v[16:17]
	v_cndmask_b32_e64 v155, v35, 1.0, vcc
	v_add_u32_e32 v143, s16, v59
	v_lshl_add_u64 v[134:135], s[40:41], 0, v[50:51]
	v_mov_b64_e32 v[30:31], v[14:15]
	v_mov_b64_e32 v[28:29], v[12:13]
	v_mov_b64_e32 v[26:27], v[10:11]
	v_mov_b64_e32 v[24:25], v[8:9]
	v_mov_b64_e32 v[22:23], v[6:7]
	v_mov_b64_e32 v[20:21], v[4:5]
	v_mov_b64_e32 v[18:19], v[2:3]
	s_mov_b32 s4, 0x15cf1000
	s_waitcnt lgkmcnt(0)
	v_readlane_b32 s37, v252, 19
	v_readlane_b32 s38, v252, 20
	v_readlane_b32 s39, v252, 21
	v_readlane_b32 s42, v252, 24
	v_readlane_b32 s43, v252, 25
.Lrotmla_head:
	s_barrier
.LBB0_919:
	ds_read_b128 v[34:37], v149 offset:32768
	ds_read_b128 v[38:41], v149 offset:40960
	ds_read_b128 v[162:165], v152 offset:32768
	ds_read_b128 v[166:169], v152 offset:40960
	v_exp_f32_e32 v161, v114
	v_add_f32_e32 v114, 0, v128
	s_waitcnt lgkmcnt(3)
	v_mfma_f32_32x32x16_bf16 v[50:65], v[34:37], v[78:81], 0
	v_add_f32_e32 v114, v138, v114
	v_add_f32_e32 v114, v129, v114
	v_add_f32_e32 v114, v139, v114
	v_add_f32_e32 v114, v136, v114
	v_add_f32_e32 v114, v159, v114
	v_add_f32_e32 v114, v137, v114
	v_add_f32_e32 v114, v160, v114
	s_waitcnt lgkmcnt(2)
	v_mfma_f32_32x32x16_bf16 v[34:49], v[38:41], v[78:81], 0
	v_add_f32_e32 v114, v120, v114
	v_add_f32_e32 v114, v123, v114
	v_add_f32_e32 v114, v121, v114
	v_add_f32_e32 v114, v124, v114
	v_exp_f32_e32 v119, v116
	v_add_f32_e32 v114, v122, v114
	v_exp_f32_e32 v158, v117
	s_waitcnt lgkmcnt(1)
	v_mfma_f32_32x32x16_bf16 v[50:65], v[162:165], v[74:77], v[50:65]
	v_add_f32_e32 v114, v125, v114
	v_add_f32_e32 v114, v126, v114
	v_add_f32_e32 v114, v127, v114
	v_exp_f32_e32 v110, v110
	v_add_f32_e32 v114, v119, v114
	v_exp_f32_e32 v111, v111
	v_add_f32_e32 v114, v158, v114
	s_waitcnt lgkmcnt(0)
	v_mfma_f32_32x32x16_bf16 v[34:49], v[166:169], v[74:77], v[34:49]
	ds_read_b128 v[162:165], v151 offset:32768
	ds_read_b128 v[166:169], v151 offset:40960
	v_exp_f32_e32 v106, v106
	v_add_f32_e32 v114, v161, v114
	v_exp_f32_e32 v107, v107
	v_exp_f32_e32 v104, v104
	v_exp_f32_e32 v105, v105
	v_exp_f32_e32 v112, v112
	s_waitcnt lgkmcnt(1)
	v_mfma_f32_32x32x16_bf16 v[50:65], v[162:165], v[70:73], v[50:65]
	v_exp_f32_e32 v113, v113
	v_exp_f32_e32 v108, v108
	v_exp_f32_e32 v109, v109
	v_exp_f32_e32 v102, v102
	v_exp_f32_e32 v103, v103
	s_waitcnt lgkmcnt(0)
	v_mfma_f32_32x32x16_bf16 v[34:49], v[166:169], v[70:73], v[34:49]
	ds_read_b128 v[162:165], v150 offset:32768
	ds_read_b128 v[166:169], v150 offset:40960
	s_waitcnt lgkmcnt(1)
	v_mfma_f32_32x32x16_bf16 v[50:65], v[162:165], v[66:69], v[50:65]
	s_waitcnt lgkmcnt(0)
	v_mfma_f32_32x32x16_bf16 v[34:49], v[166:169], v[66:69], v[34:49]
	ds_read_b128 v[162:165], v153 offset:32768
	ds_read_b128 v[166:169], v153 offset:40960
	s_waitcnt lgkmcnt(1)
	v_mfma_f32_32x32x16_bf16 v[50:65], v[162:165], v[86:89], v[50:65]
	s_waitcnt lgkmcnt(0)
	v_mfma_f32_32x32x16_bf16 v[34:49], v[166:169], v[86:89], v[34:49]
	ds_read_b128 v[162:165], v154 offset:32768
	ds_read_b128 v[166:169], v154 offset:40960
	s_waitcnt lgkmcnt(1)
	v_mfma_f32_32x32x16_bf16 v[50:65], v[162:165], v[82:85], v[50:65]
	v_exp_f32_e32 v162, v115
	s_nop 0
	v_add_f32_e32 v114, v162, v114
	v_add_f32_e32 v114, v110, v114
	v_add_f32_e32 v114, v111, v114
	v_add_f32_e32 v114, v106, v114
	v_add_f32_e32 v114, v107, v114
	v_add_f32_e32 v114, v104, v114
	v_add_f32_e32 v114, v105, v114
	s_waitcnt lgkmcnt(0)
	v_mfma_f32_32x32x16_bf16 v[34:49], v[166:169], v[82:85], v[34:49]
	v_add_f32_e32 v114, v112, v114
	v_add_f32_e32 v114, v113, v114
	v_add_f32_e32 v114, v108, v114
	v_add_f32_e32 v114, v109, v114
	v_add_f32_e32 v114, v102, v114
	v_add_f32_e32 v156, v103, v114
	v_mov_b32_e32 v157, v156
	v_cvt_pk_bf16_f32 v114, v128, v138
	v_cvt_pk_bf16_f32 v115, v129, v139
	v_cvt_pk_bf16_f32 v116, v136, v159
	v_cvt_pk_bf16_f32 v117, v137, v160
	v_cvt_pk_bf16_f32 v120, v120, v123
	v_cvt_pk_bf16_f32 v121, v121, v124
	v_cvt_pk_bf16_f32 v122, v122, v125
	v_cvt_pk_bf16_f32 v123, v126, v127
	v_cvt_pk_bf16_f32 v124, v119, v158
	v_cvt_pk_bf16_f32 v125, v161, v162
	v_cvt_pk_bf16_f32 v126, v110, v111
	v_cvt_pk_bf16_f32 v127, v106, v107
	v_cvt_pk_bf16_f32 v158, v104, v105
	v_cvt_pk_bf16_f32 v159, v112, v113
	v_cvt_pk_bf16_f32 v160, v108, v109
	s_nop 1
	v_permlane32_swap_b32_e32 v156, v157
	v_permlane32_swap_b32_e32 v114, v116
	v_cvt_pk_bf16_f32 v161, v102, v103
	v_permlane32_swap_b32_e32 v158, v160
	v_permlane32_swap_b32_e32 v115, v117
	v_permlane32_swap_b32_e32 v120, v122
	v_permlane32_swap_b32_e32 v121, v123
	v_permlane32_swap_b32_e32 v124, v126
	v_permlane32_swap_b32_e32 v125, v127
	v_permlane32_swap_b32_e32 v159, v161
	v_lshl_add_u64 v[138:139], v[134:135], 0, s[14:15]
	v_add_co_u32_e32 v102, vcc, s4, v138
	v_lshl_add_u64 v[136:137], v[132:133], 0, s[14:15]
	s_nop 0
	v_addc_co_u32_e32 v103, vcc, 0, v139, vcc
	v_add_co_u32_e32 v106, vcc, s4, v136
	s_mov_b32 s8, 0x15d01000
	s_nop 0
	v_addc_co_u32_e32 v107, vcc, 0, v137, vcc
	v_add_co_u32_e32 v110, vcc, s8, v136
	global_load_dwordx4 v[102:105], v[102:103], off offset:3072
	s_nop 0
	v_addc_co_u32_e32 v111, vcc, 0, v137, vcc
	global_load_dwordx4 v[106:109], v[106:107], off offset:2304
	s_nop 0
	global_load_dwordx4 v[110:113], v[110:111], off offset:2304
	ds_read_b64_tr_b16 v[162:163], v145 offset:0
	ds_read_b64_tr_b16 v[164:165], v145 offset:0x400
	ds_read_b64_tr_b16 v[166:167], v145 offset:0x800
	ds_read_b64_tr_b16 v[168:169], v145 offset:0xc00
	ds_read_b64_tr_b16 v[170:171], v145 offset:0x1000
	ds_read_b64_tr_b16 v[172:173], v145 offset:0x1400
	ds_read_b64_tr_b16 v[174:175], v145 offset:0x1800
	ds_read_b64_tr_b16 v[176:177], v145 offset:0x1c00
	s_waitcnt lgkmcnt(0)
	s_nop 0
	v_mfma_f32_32x32x16_bf16 v[2:17], v[114:117], v[162:165], v[2:17]
	ds_read_b64_tr_b16 v[162:163], v145 offset:0x200
	ds_read_b64_tr_b16 v[164:165], v145 offset:0x600
	v_mfma_f32_32x32x16_bf16 v[2:17], v[120:123], v[166:169], v[2:17]
	ds_read_b64_tr_b16 v[166:167], v145 offset:0xa00
	ds_read_b64_tr_b16 v[168:169], v145 offset:0xe00
	v_mfma_f32_32x32x16_bf16 v[2:17], v[124:127], v[170:173], v[2:17]
	ds_read_b64_tr_b16 v[170:171], v145 offset:0x1200
	ds_read_b64_tr_b16 v[172:173], v145 offset:0x1600
	v_mfma_f32_32x32x16_bf16 v[2:17], v[158:161], v[174:177], v[2:17]
	ds_read_b64_tr_b16 v[174:175], v145 offset:0x1a00
	ds_read_b64_tr_b16 v[176:177], v145 offset:0x1e00
	s_waitcnt lgkmcnt(0)
	v_mfma_f32_32x32x16_bf16 v[18:33], v[114:117], v[162:165], v[18:33]
	v_max_f32_e32 v114, v51, v51
	v_max_f32_e32 v115, v50, v50
	v_max_f32_e32 v114, v115, v114
	v_max3_f32 v114, v114, v52, v53
	v_max3_f32 v114, v114, v54, v55
	v_max3_f32 v114, v114, v56, v57
	v_max3_f32 v114, v114, v58, v59
	v_max3_f32 v114, v114, v60, v61
	v_max3_f32 v114, v114, v62, v63
	v_mfma_f32_32x32x16_bf16 v[18:33], v[120:123], v[166:169], v[18:33]
	v_max3_f32 v114, v114, v64, v65
	v_max3_f32 v114, v114, v34, v35
	v_max3_f32 v114, v114, v36, v37
	v_max3_f32 v114, v114, v38, v39
	v_max3_f32 v114, v114, v40, v41
	v_max3_f32 v114, v114, v42, v43
	v_max3_f32 v114, v114, v44, v45
	v_max3_f32 v114, v114, v46, v47
	v_mfma_f32_32x32x16_bf16 v[18:33], v[124:127], v[170:173], v[18:33]
	v_max3_f32 v114, v114, v48, v49
	v_mov_b32_e32 v115, v114
	s_nop 1
	v_permlane32_swap_b32_e32 v114, v115
	v_max_f32_e32 v115, v115, v115
	v_max_f32_e32 v114, v114, v114
	v_max_f32_e32 v114, v114, v115
	v_sub_f32_e32 v115, v114, v118
	v_cmp_ge_f32_e32 vcc, s72, v115
	v_max_f32_e32 v115, v118, v118
	v_max_f32_e32 v114, v115, v114
	v_mfma_f32_32x32x16_bf16 v[18:33], v[158:161], v[174:177], v[18:33]
	v_sub_f32_e32 v115, v118, v114
	v_mul_f32_e32 v115, 0x3e16c740, v115
	v_exp_f32_e32 v115, v115
	s_cmp_eq_u64 vcc, exec
	s_cselect_b64 s[8:9], -1, 0
	s_barrier
	s_waitcnt vmcnt(3)
	v_cndmask_b32_e64 v158, v115, 1.0, s[8:9]
	v_cmp_gt_f32_e32 vcc, 1.0, v158
	s_waitcnt vmcnt(3)
	ds_write_b128 v146, v[90:93]
	ds_write_b128 v147, v[98:101] offset:16384
	ds_write_b128 v148, v[94:97] offset:16384
	s_cbranch_vccz .LBB0_923
	s_and_saveexec_b64 s[16:17], s[0:1]
	ds_write_b32 v142, v158 offset:49280
	s_or_b64 exec, exec, s[16:17]
	s_waitcnt lgkmcnt(0)
	v_add_u32_e32 v115, v131, v0
	ds_read_b128 v[120:123], v115 offset:49376
	ds_read_b128 v[124:127], v115 offset:49344
	ds_read_b128 v[160:163], v115 offset:49312
	ds_read_b128 v[164:167], v115 offset:49280
	s_waitcnt lgkmcnt(3)
	v_pk_mul_f32 v[14:15], v[14:15], v[120:121]
	s_waitcnt lgkmcnt(2)
	v_pk_mul_f32 v[10:11], v[10:11], v[124:125]
	s_waitcnt lgkmcnt(1)
	v_pk_mul_f32 v[6:7], v[6:7], v[160:161]
	v_pk_mul_f32 v[16:17], v[16:17], v[122:123]
	v_pk_mul_f32 v[12:13], v[12:13], v[126:127]
	v_pk_mul_f32 v[8:9], v[8:9], v[162:163]
	s_waitcnt lgkmcnt(0)
	v_pk_mul_f32 v[4:5], v[4:5], v[166:167]
	v_pk_mul_f32 v[2:3], v[2:3], v[164:165]
	v_pk_mul_f32 v[30:31], v[30:31], v[120:121]
	v_pk_mul_f32 v[26:27], v[26:27], v[124:125]
	v_pk_mul_f32 v[22:23], v[22:23], v[160:161]
	v_pk_mul_f32 v[32:33], v[32:33], v[122:123]
	v_pk_mul_f32 v[28:29], v[28:29], v[126:127]
	v_pk_mul_f32 v[24:25], v[24:25], v[162:163]
	v_pk_mul_f32 v[20:21], v[20:21], v[166:167]
	v_pk_mul_f32 v[18:19], v[18:19], v[164:165]

.LBB0_929:
	v_cndmask_b32_e64 v118, v114, v159, s[8:9]
	v_mul_f32_e32 v102, 0xbe16c740, v118
	v_pk_fma_f32 v[50:51], v[50:51], s[96:97], v[102:103] op_sel_hi:[1,0,0]
	v_pk_fma_f32 v[52:53], v[52:53], s[96:97], v[102:103] op_sel_hi:[1,0,0]
	v_pk_fma_f32 v[54:55], v[54:55], s[96:97], v[102:103] op_sel_hi:[1,0,0]
	v_pk_fma_f32 v[56:57], v[56:57], s[96:97], v[102:103] op_sel_hi:[1,0,0]
	v_pk_fma_f32 v[58:59], v[58:59], s[96:97], v[102:103] op_sel_hi:[1,0,0]
	v_pk_fma_f32 v[60:61], v[60:61], s[96:97], v[102:103] op_sel_hi:[1,0,0]
	v_pk_fma_f32 v[62:63], v[62:63], s[96:97], v[102:103] op_sel_hi:[1,0,0]
	v_pk_fma_f32 v[64:65], v[64:65], s[96:97], v[102:103] op_sel_hi:[1,0,0]
	v_exp_f32_e32 v128, v50
	v_exp_f32_e32 v138, v51
	v_exp_f32_e32 v129, v52
	v_exp_f32_e32 v139, v53
	v_exp_f32_e32 v136, v54
	v_exp_f32_e32 v159, v55
	v_exp_f32_e32 v137, v56
	v_exp_f32_e32 v160, v57
	v_exp_f32_e32 v120, v58
	v_exp_f32_e32 v123, v59
	v_exp_f32_e32 v121, v60
	v_exp_f32_e32 v124, v61
	v_exp_f32_e32 v122, v62
	v_exp_f32_e32 v125, v63
	v_exp_f32_e32 v126, v64
	v_exp_f32_e32 v127, v65
	v_pk_fma_f32 v[116:117], v[34:35], s[96:97], v[102:103] op_sel_hi:[1,0,0]
	v_add_f32_e32 v34, v156, v157
	v_fmac_f32_e32 v34, v155, v144
	v_add_f32_e32 v144, v161, v162
	v_pk_fma_f32 v[114:115], v[36:37], s[96:97], v[102:103] op_sel_hi:[1,0,0]
	v_pk_fma_f32 v[110:111], v[38:39], s[96:97], v[102:103] op_sel_hi:[1,0,0]
	v_pk_fma_f32 v[106:107], v[40:41], s[96:97], v[102:103] op_sel_hi:[1,0,0]
	v_pk_fma_f32 v[104:105], v[42:43], s[96:97], v[102:103] op_sel_hi:[1,0,0]
	v_pk_fma_f32 v[112:113], v[44:45], s[96:97], v[102:103] op_sel_hi:[1,0,0]
	v_pk_fma_f32 v[108:109], v[46:47], s[96:97], v[102:103] op_sel_hi:[1,0,0]
	v_pk_fma_f32 v[102:103], v[48:49], s[96:97], v[102:103] op_sel_hi:[1,0,0]
	v_fmac_f32_e32 v144, v34, v158
	s_add_i32 s24, s24, 2
	v_lshl_add_u64 v[132:133], v[132:133], 0, s[2:3]
	v_lshl_add_u64 v[134:135], v[134:135], 0, s[2:3]
	s_and_b64 vcc, exec, s[16:17]
	s_waitcnt lgkmcnt(0)
	s_cbranch_vccnz .Lrotmla_exit
	v_mov_b32_e32 v155, v119
	s_branch .Lrotmla_head
